# q-projection rope epilogue pipelining depth raised from 3 to 6 steps
# speedup vs baseline: 1.0084x; 1.0084x over previous
; DI u16 f2bf(float x) { return (u16)(pack2(x, 0.f) & 0xffffu); }
; DI int crow(int i, int h) { return (i & 3) + 8 * (i >> 2) + 4 * h; }
; __global__ void __launch_bounds__(256, 2) fwd_megakernel(Params p) {
;     ...
;           if (is_rope) {
; #pragma unroll
;             for (int mt = 0; mt < 2; mt++)
; #pragma unroll
;               for (int i = 0; i < 16; i++) {
;                 const int m = m0 + wm * 64 + mt * 32 + crow(i, h);
;                 const float v0 = acc[mt][0][i], v1 = acc[mt][1][i];
;                 const int pos = tok_pos(m);
;                 const float c = ct[pos * 32 + r], s = st[pos * 32 + r];
;                 Q[(long)m * 1536 + nw0 + r] = f2bf((v0 * c - v1 * s) * QSCALE);
;                 Q[(long)m * 1536 + nw0 + 32 + r] = f2bf((v1 * c + v0 * s) * QSCALE);
;               }
.LBB0_567:
	s_andn2_saveexec_b64 s[52:53], s[0:1]
	s_cbranch_execz .LBB0_548
	v_cmp_gt_i32_e32 vcc, s33, v99
	v_or_b32_e32 v100, 0x400, v100
	s_nop 0
	v_cndmask_b32_e32 v100, v100, v99, vcc
	v_lshl_or_b32 v100, v100, 5, v69
	v_ashrrev_i32_e32 v101, 31, v100
	v_lshlrev_b64 v[100:101], 2, v[100:101]
	v_lshl_add_u64 v[102:103], s[34:35], 0, v[100:101]
	v_lshl_add_u64 v[100:101], s[36:37], 0, v[100:101]
	global_load_dword v228, v[102:103], off
	v_cmp_gt_i32_e32 vcc, s33, v98
	global_load_dword v229, v[100:101], off
	s_waitcnt vmcnt(0)
	v_mul_f32_e32 v100, v50, v229
	v_fma_f32 v100, v34, v228, -v100
	v_mul_f32_e32 v34, v34, v229
	v_mul_f32_e32 v100, 0x3dd53b94, v100
	v_fmac_f32_e32 v34, v50, v228
	v_cvt_pk_bf16_f32 v104, v100, s0
	v_mad_i64_i32 v[100:101], s[0:1], v99, s85, v[66:67]
	v_mul_f32_e32 v34, 0x3dd53b94, v34
	s_nop 0
	v_cvt_pk_bf16_f32 v34, v34, s0
	global_store_short v[100:101], v34, off offset:64
	v_and_or_b32 v34, v98, 5, v210
	v_cndmask_b32_e32 v34, v34, v98, vcc
	global_store_short v[100:101], v104, off
	v_lshl_or_b32 v100, v34, 5, v69
	v_ashrrev_i32_e32 v101, 31, v100
	v_lshlrev_b64 v[100:101], 2, v[100:101]
	v_lshl_add_u64 v[102:103], s[34:35], 0, v[100:101]
	v_lshl_add_u64 v[100:101], s[36:37], 0, v[100:101]
	global_load_dword v34, v[102:103], off
	global_load_dword v50, v[100:101], off
	v_cmp_gt_i32_e32 vcc, s33, v97
	s_waitcnt vmcnt(0)
	v_mul_f32_e32 v99, v51, v50
	v_fma_f32 v99, v35, v34, -v99
	v_mul_f32_e32 v35, v35, v50
	v_mul_f32_e32 v99, 0x3dd53b94, v99
	v_fmac_f32_e32 v35, v51, v34
	v_cvt_pk_bf16_f32 v100, v99, s0
	v_mad_i64_i32 v[98:99], s[0:1], v98, s85, v[66:67]
	v_mul_f32_e32 v34, 0x3dd53b94, v35
	s_nop 0
	v_cvt_pk_bf16_f32 v34, v34, s0
	global_store_short v[98:99], v34, off offset:64
	v_and_or_b32 v34, v97, 6, v210
	v_cndmask_b32_e32 v34, v34, v97, vcc
	v_lshl_or_b32 v34, v34, 5, v69
	v_ashrrev_i32_e32 v35, 31, v34
	v_lshlrev_b64 v[34:35], 2, v[34:35]
	v_lshl_add_u64 v[50:51], s[34:35], 0, v[34:35]
	v_lshl_add_u64 v[34:35], s[36:37], 0, v[34:35]
	global_load_dword v50, v[50:51], off
	v_cmp_gt_i32_e32 vcc, s33, v96
	global_load_dword v51, v[34:35], off
	s_waitcnt vmcnt(0)
	v_mul_f32_e32 v34, v52, v51
	v_fma_f32 v34, v36, v50, -v34
	v_mul_f32_e32 v36, v36, v51
	v_mul_f32_e32 v34, 0x3dd53b94, v34
	v_fmac_f32_e32 v36, v52, v50
	global_store_short v[98:99], v100, off
	v_cvt_pk_bf16_f32 v98, v34, s0
	v_mad_i64_i32 v[34:35], s[0:1], v97, s85, v[66:67]
	v_mul_f32_e32 v36, 0x3dd53b94, v36
	s_nop 0
	v_cvt_pk_bf16_f32 v36, v36, s0
	global_store_short v[34:35], v98, off
	global_store_short v[34:35], v36, off offset:64
	v_and_or_b32 v34, v96, 7, v210
	v_cndmask_b32_e32 v34, v34, v96, vcc
	v_lshl_or_b32 v34, v34, 5, v69
	v_ashrrev_i32_e32 v35, 31, v34
	v_lshlrev_b64 v[34:35], 2, v[34:35]
	v_lshl_add_u64 v[50:51], s[34:35], 0, v[34:35]
	v_lshl_add_u64 v[34:35], s[36:37], 0, v[34:35]
	global_load_dword v36, v[50:51], off
	v_cmp_gt_i32_e32 vcc, s33, v95
	global_load_dword v50, v[34:35], off
	s_waitcnt vmcnt(0)
	v_mul_f32_e32 v34, v53, v50
	v_fma_f32 v34, v37, v36, -v34
	v_mul_f32_e32 v37, v37, v50
	v_mul_f32_e32 v34, 0x3dd53b94, v34
	v_fmac_f32_e32 v37, v53, v36
	v_cvt_pk_bf16_f32 v51, v34, s0
	v_mad_i64_i32 v[34:35], s[0:1], v96, s85, v[66:67]
	v_mul_f32_e32 v36, 0x3dd53b94, v37
	s_nop 0
	v_cvt_pk_bf16_f32 v36, v36, s0
	global_store_short v[34:35], v51, off
	global_store_short v[34:35], v36, off offset:64
	v_and_or_b32 v34, v95, 12, v210
	v_cndmask_b32_e32 v34, v34, v95, vcc
	v_lshl_or_b32 v34, v34, 5, v69
	v_ashrrev_i32_e32 v35, 31, v34
	v_lshlrev_b64 v[34:35], 2, v[34:35]
	v_lshl_add_u64 v[36:37], s[34:35], 0, v[34:35]
	v_lshl_add_u64 v[34:35], s[36:37], 0, v[34:35]
	global_load_dword v234, v[36:37], off
	v_cmp_gt_i32_e32 vcc, s33, v94
	global_load_dword v235, v[34:35], off
	v_and_or_b32 v34, v94, 13, v210
	v_cndmask_b32_e32 v34, v34, v94, vcc
	v_lshl_or_b32 v34, v34, 5, v69
	v_ashrrev_i32_e32 v35, 31, v34
	v_lshlrev_b64 v[34:35], 2, v[34:35]
	v_lshl_add_u64 v[36:37], s[34:35], 0, v[34:35]
	v_lshl_add_u64 v[34:35], s[36:37], 0, v[34:35]
	global_load_dword v236, v[36:37], off
	v_cmp_gt_i32_e32 vcc, s33, v93
	global_load_dword v237, v[34:35], off
	v_and_or_b32 v34, v93, 14, v210
	v_cndmask_b32_e32 v34, v34, v93, vcc
	v_lshl_or_b32 v34, v34, 5, v69
	v_ashrrev_i32_e32 v35, 31, v34
	v_lshlrev_b64 v[34:35], 2, v[34:35]
	v_lshl_add_u64 v[36:37], s[34:35], 0, v[34:35]
	v_lshl_add_u64 v[34:35], s[36:37], 0, v[34:35]
	global_load_dword v238, v[36:37], off
	v_cmp_gt_i32_e32 vcc, s33, v92
	global_load_dword v239, v[34:35], off
	v_and_or_b32 v34, v92, 15, v210
	v_cndmask_b32_e32 v34, v34, v92, vcc
	v_lshl_or_b32 v34, v34, 5, v69
	v_ashrrev_i32_e32 v35, 31, v34
	v_lshlrev_b64 v[34:35], 2, v[34:35]
	v_lshl_add_u64 v[36:37], s[34:35], 0, v[34:35]
	v_lshl_add_u64 v[34:35], s[36:37], 0, v[34:35]
	global_load_dword v228, v[36:37], off
	v_cmp_gt_i32_e32 vcc, s33, v91
	global_load_dword v229, v[34:35], off
	v_and_or_b32 v34, v91, 20, v210
	v_cndmask_b32_e32 v34, v34, v91, vcc
	v_lshl_or_b32 v34, v34, 5, v69
	v_ashrrev_i32_e32 v35, 31, v34
	v_lshlrev_b64 v[34:35], 2, v[34:35]
	v_lshl_add_u64 v[36:37], s[34:35], 0, v[34:35]
	v_lshl_add_u64 v[34:35], s[36:37], 0, v[34:35]
	global_load_dword v230, v[36:37], off
	v_cmp_gt_i32_e32 vcc, s33, v90
	global_load_dword v231, v[34:35], off
	v_and_or_b32 v34, v90, 21, v210
	v_cndmask_b32_e32 v34, v34, v90, vcc
	v_lshl_or_b32 v34, v34, 5, v69
	v_ashrrev_i32_e32 v35, 31, v34
	v_lshlrev_b64 v[34:35], 2, v[34:35]
	v_lshl_add_u64 v[36:37], s[34:35], 0, v[34:35]
	v_lshl_add_u64 v[34:35], s[36:37], 0, v[34:35]
	global_load_dword v232, v[36:37], off
	v_cmp_gt_i32_e32 vcc, s33, v89
	global_load_dword v233, v[34:35], off
	s_waitcnt vmcnt(10)
; DI u16 f2bf(float x) { return (u16)(pack2(x, 0.f) & 0xffffu); }
; DI int crow(int i, int h) { return (i & 3) + 8 * (i >> 2) + 4 * h; }
; __global__ void __launch_bounds__(256, 2) fwd_megakernel(Params p) {
;     ...
;           if (is_rope) {
; #pragma unroll
;             for (int mt = 0; mt < 2; mt++)
; #pragma unroll
;               for (int i = 0; i < 16; i++) {
;                 const int m = m0 + wm * 64 + mt * 32 + crow(i, h);
;                 const float v0 = acc[mt][0][i], v1 = acc[mt][1][i];
;                 const int pos = tok_pos(m);
;                 const float c = ct[pos * 32 + r], s = st[pos * 32 + r];
;                 Q[(long)m * 1536 + nw0 + r] = f2bf((v0 * c - v1 * s) * QSCALE);
;                 Q[(long)m * 1536 + nw0 + 32 + r] = f2bf((v1 * c + v0 * s) * QSCALE);
;               }
	v_mul_f32_e32 v34, v54, v235
	v_fma_f32 v34, v38, v234, -v34
	v_mul_f32_e32 v37, v38, v235
	v_mul_f32_e32 v34, 0x3dd53b94, v34
	v_fmac_f32_e32 v37, v54, v234
	v_cvt_pk_bf16_f32 v50, v34, s0
	v_mad_i64_i32 v[34:35], s[0:1], v95, s85, v[66:67]
	v_mul_f32_e32 v36, 0x3dd53b94, v37
	s_nop 0
	v_cvt_pk_bf16_f32 v36, v36, s0
	global_store_short v[34:35], v50, off
	global_store_short v[34:35], v36, off offset:64
	v_and_or_b32 v34, v89, 22, v210
	v_cndmask_b32_e32 v34, v34, v89, vcc
	v_lshl_or_b32 v34, v34, 5, v69
	v_ashrrev_i32_e32 v35, 31, v34
	v_lshlrev_b64 v[34:35], 2, v[34:35]
	v_lshl_add_u64 v[36:37], s[34:35], 0, v[34:35]
	v_lshl_add_u64 v[34:35], s[36:37], 0, v[34:35]
	global_load_dword v234, v[36:37], off
	v_cmp_gt_i32_e32 vcc, s33, v88
	global_load_dword v235, v[34:35], off
	s_waitcnt vmcnt(12)
	v_mul_f32_e32 v34, v55, v237
	v_fma_f32 v34, v39, v236, -v34
	v_mul_f32_e32 v37, v39, v237
	v_mul_f32_e32 v34, 0x3dd53b94, v34
	v_fmac_f32_e32 v37, v55, v236
	v_cvt_pk_bf16_f32 v38, v34, s0
	v_mad_i64_i32 v[34:35], s[0:1], v94, s85, v[66:67]
	v_mul_f32_e32 v36, 0x3dd53b94, v37
	s_nop 0
	v_cvt_pk_bf16_f32 v36, v36, s0
	global_store_short v[34:35], v38, off
	global_store_short v[34:35], v36, off offset:64
	v_and_or_b32 v34, v88, 23, v210
	v_cndmask_b32_e32 v34, v34, v88, vcc
	v_lshl_or_b32 v34, v34, 5, v69
	v_ashrrev_i32_e32 v35, 31, v34
	v_lshlrev_b64 v[34:35], 2, v[34:35]
	v_lshl_add_u64 v[36:37], s[34:35], 0, v[34:35]
	v_lshl_add_u64 v[34:35], s[36:37], 0, v[34:35]
	global_load_dword v236, v[36:37], off
	v_cmp_gt_i32_e32 vcc, s33, v87
	global_load_dword v237, v[34:35], off
	s_waitcnt vmcnt(14)
	v_mul_f32_e32 v34, v56, v239
	v_fma_f32 v34, v40, v238, -v34
	v_mul_f32_e32 v37, v40, v239
	v_mul_f32_e32 v34, 0x3dd53b94, v34
	v_fmac_f32_e32 v37, v56, v238
	v_cvt_pk_bf16_f32 v38, v34, s0
	v_mad_i64_i32 v[34:35], s[0:1], v93, s85, v[66:67]
	v_mul_f32_e32 v36, 0x3dd53b94, v37
	s_nop 0
	v_cvt_pk_bf16_f32 v36, v36, s0
	global_store_short v[34:35], v38, off
	global_store_short v[34:35], v36, off offset:64
	v_and_or_b32 v34, v87, 28, v210
	v_cndmask_b32_e32 v34, v34, v87, vcc
	v_lshl_or_b32 v34, v34, 5, v69
	v_ashrrev_i32_e32 v35, 31, v34
	v_lshlrev_b64 v[34:35], 2, v[34:35]
	v_lshl_add_u64 v[36:37], s[34:35], 0, v[34:35]
	v_lshl_add_u64 v[34:35], s[36:37], 0, v[34:35]
	global_load_dword v238, v[36:37], off
	v_cmp_gt_i32_e32 vcc, s33, v86
	global_load_dword v239, v[34:35], off
	s_waitcnt vmcnt(16)
	v_mul_f32_e32 v34, v57, v229
	v_fma_f32 v34, v41, v228, -v34
	v_mul_f32_e32 v37, v41, v229
	v_mul_f32_e32 v34, 0x3dd53b94, v34
	v_fmac_f32_e32 v37, v57, v228
	v_cvt_pk_bf16_f32 v38, v34, s0
	v_mad_i64_i32 v[34:35], s[0:1], v92, s85, v[66:67]
	v_mul_f32_e32 v36, 0x3dd53b94, v37
	s_nop 0
	v_cvt_pk_bf16_f32 v36, v36, s0
	global_store_short v[34:35], v38, off
	global_store_short v[34:35], v36, off offset:64
	v_and_or_b32 v34, v86, 29, v210
	v_cndmask_b32_e32 v34, v34, v86, vcc
	v_lshl_or_b32 v34, v34, 5, v69
	v_ashrrev_i32_e32 v35, 31, v34
	v_lshlrev_b64 v[34:35], 2, v[34:35]
	v_lshl_add_u64 v[36:37], s[34:35], 0, v[34:35]
	v_lshl_add_u64 v[34:35], s[36:37], 0, v[34:35]
	global_load_dword v228, v[36:37], off
	v_cmp_gt_i32_e32 vcc, s33, v85
	global_load_dword v229, v[34:35], off
	s_waitcnt vmcnt(18)
	v_mul_f32_e32 v34, v58, v231
	v_fma_f32 v34, v42, v230, -v34
	v_mul_f32_e32 v37, v42, v231
	v_mul_f32_e32 v34, 0x3dd53b94, v34
	v_fmac_f32_e32 v37, v58, v230
	v_cvt_pk_bf16_f32 v38, v34, s0
	v_mad_i64_i32 v[34:35], s[0:1], v91, s85, v[66:67]
	v_mul_f32_e32 v36, 0x3dd53b94, v37
	s_nop 0
	v_cvt_pk_bf16_f32 v36, v36, s0
	global_store_short v[34:35], v38, off
	global_store_short v[34:35], v36, off offset:64
	v_and_or_b32 v34, v85, 30, v210
	v_cndmask_b32_e32 v34, v34, v85, vcc
	v_lshl_or_b32 v34, v34, 5, v69
	v_ashrrev_i32_e32 v35, 31, v34
	v_lshlrev_b64 v[34:35], 2, v[34:35]
	v_lshl_add_u64 v[36:37], s[34:35], 0, v[34:35]
	v_lshl_add_u64 v[34:35], s[36:37], 0, v[34:35]
	global_load_dword v230, v[36:37], off
	v_cmp_gt_i32_e32 vcc, s33, v84
	global_load_dword v231, v[34:35], off
	s_waitcnt vmcnt(20)
	v_mul_f32_e32 v34, v59, v233
	v_fma_f32 v34, v43, v232, -v34
	v_mul_f32_e32 v37, v43, v233
	v_mul_f32_e32 v34, 0x3dd53b94, v34
	v_fmac_f32_e32 v37, v59, v232
	v_cvt_pk_bf16_f32 v38, v34, s0
	v_mad_i64_i32 v[34:35], s[0:1], v90, s85, v[66:67]
	v_mul_f32_e32 v36, 0x3dd53b94, v37
	s_nop 0
	v_cvt_pk_bf16_f32 v36, v36, s0
	global_store_short v[34:35], v38, off
	global_store_short v[34:35], v36, off offset:64
	v_and_or_b32 v34, v84, 31, v210
	v_cndmask_b32_e32 v34, v34, v84, vcc
	v_lshl_or_b32 v34, v34, 5, v69
	v_ashrrev_i32_e32 v35, 31, v34
	v_lshlrev_b64 v[34:35], 2, v[34:35]
	v_lshl_add_u64 v[36:37], s[34:35], 0, v[34:35]
	v_lshl_add_u64 v[34:35], s[36:37], 0, v[34:35]
	global_load_dword v232, v[36:37], off
	v_cmp_gt_i32_e32 vcc, s33, v83
	global_load_dword v233, v[34:35], off
	s_waitcnt vmcnt(20)
	v_mul_f32_e32 v34, v60, v235
	v_fma_f32 v34, v44, v234, -v34
	v_mul_f32_e32 v37, v44, v235
	v_mul_f32_e32 v34, 0x3dd53b94, v34
	v_fmac_f32_e32 v37, v60, v234
	v_cvt_pk_bf16_f32 v38, v34, s0
	v_mad_i64_i32 v[34:35], s[0:1], v89, s85, v[66:67]
	v_mul_f32_e32 v36, 0x3dd53b94, v37
	s_nop 0
	v_cvt_pk_bf16_f32 v36, v36, s0
	global_store_short v[34:35], v38, off
	global_store_short v[34:35], v36, off offset:64
	v_and_or_b32 v34, v83, 36, v210
	v_cndmask_b32_e32 v34, v34, v83, vcc
	v_lshl_or_b32 v34, v34, 5, v69
	v_ashrrev_i32_e32 v35, 31, v34
	v_lshlrev_b64 v[34:35], 2, v[34:35]
	v_lshl_add_u64 v[36:37], s[34:35], 0, v[34:35]
	v_lshl_add_u64 v[34:35], s[36:37], 0, v[34:35]
	global_load_dword v234, v[36:37], off
	v_cmp_gt_i32_e32 vcc, s33, v82
	global_load_dword v235, v[34:35], off
	s_waitcnt vmcnt(20)
; DI u16 f2bf(float x) { return (u16)(pack2(x, 0.f) & 0xffffu); }
; DI int crow(int i, int h) { return (i & 3) + 8 * (i >> 2) + 4 * h; }
; __global__ void __launch_bounds__(256, 2) fwd_megakernel(Params p) {
;     ...
;           if (is_rope) {
; #pragma unroll
;             for (int mt = 0; mt < 2; mt++)
; #pragma unroll
;               for (int i = 0; i < 16; i++) {
;                 const int m = m0 + wm * 64 + mt * 32 + crow(i, h);
;                 const float v0 = acc[mt][0][i], v1 = acc[mt][1][i];
;                 const int pos = tok_pos(m);
;                 const float c = ct[pos * 32 + r], s = st[pos * 32 + r];
;                 Q[(long)m * 1536 + nw0 + r] = f2bf((v0 * c - v1 * s) * QSCALE);
;                 Q[(long)m * 1536 + nw0 + 32 + r] = f2bf((v1 * c + v0 * s) * QSCALE);
;               }
	v_mul_f32_e32 v34, v61, v237
	v_fma_f32 v34, v45, v236, -v34
	v_mul_f32_e32 v37, v45, v237
	v_mul_f32_e32 v34, 0x3dd53b94, v34
	v_fmac_f32_e32 v37, v61, v236
	v_cvt_pk_bf16_f32 v38, v34, s0
	v_mad_i64_i32 v[34:35], s[0:1], v88, s85, v[66:67]
	v_mul_f32_e32 v36, 0x3dd53b94, v37
	s_nop 0
	v_cvt_pk_bf16_f32 v36, v36, s0
	global_store_short v[34:35], v38, off
	global_store_short v[34:35], v36, off offset:64
	s_waitcnt vmcnt(18)
	v_mul_f32_e32 v34, v62, v239
	v_fma_f32 v34, v46, v238, -v34
	v_mul_f32_e32 v37, v46, v239
	v_mul_f32_e32 v34, 0x3dd53b94, v34
	v_fmac_f32_e32 v37, v62, v238
	v_cvt_pk_bf16_f32 v38, v34, s0
	v_mad_i64_i32 v[34:35], s[0:1], v87, s85, v[66:67]
	v_mul_f32_e32 v36, 0x3dd53b94, v37
	s_nop 0
	v_cvt_pk_bf16_f32 v36, v36, s0
	global_store_short v[34:35], v38, off
	global_store_short v[34:35], v36, off offset:64
	s_waitcnt vmcnt(16)
	v_mul_f32_e32 v34, v63, v229
	v_fma_f32 v34, v47, v228, -v34
	v_mul_f32_e32 v37, v47, v229
	v_mul_f32_e32 v34, 0x3dd53b94, v34
	v_fmac_f32_e32 v37, v63, v228
	v_cvt_pk_bf16_f32 v38, v34, s0
	v_mad_i64_i32 v[34:35], s[0:1], v86, s85, v[66:67]
	v_mul_f32_e32 v36, 0x3dd53b94, v37
	s_nop 0
	v_cvt_pk_bf16_f32 v36, v36, s0
	global_store_short v[34:35], v38, off
	global_store_short v[34:35], v36, off offset:64
	s_waitcnt vmcnt(14)
	v_mul_f32_e32 v34, v64, v231
	v_fma_f32 v34, v48, v230, -v34
	v_mul_f32_e32 v37, v48, v231
	v_mul_f32_e32 v34, 0x3dd53b94, v34
	v_fmac_f32_e32 v37, v64, v230
	v_cvt_pk_bf16_f32 v38, v34, s0
	v_mad_i64_i32 v[34:35], s[0:1], v85, s85, v[66:67]
	v_mul_f32_e32 v36, 0x3dd53b94, v37
	s_nop 0
	v_cvt_pk_bf16_f32 v36, v36, s0
	global_store_short v[34:35], v38, off
	global_store_short v[34:35], v36, off offset:64
	s_waitcnt vmcnt(12)
	v_mul_f32_e32 v34, v65, v233
	v_fma_f32 v34, v49, v232, -v34
	v_mul_f32_e32 v37, v49, v233
	v_mul_f32_e32 v34, 0x3dd53b94, v34
	v_fmac_f32_e32 v37, v65, v232
	v_cvt_pk_bf16_f32 v38, v34, s0
	v_mad_i64_i32 v[34:35], s[0:1], v84, s85, v[66:67]
	v_mul_f32_e32 v36, 0x3dd53b94, v37
	s_nop 0
	v_cvt_pk_bf16_f32 v36, v36, s0
	global_store_short v[34:35], v38, off
	global_store_short v[34:35], v36, off offset:64
	s_waitcnt vmcnt(10)
	v_mul_f32_e32 v34, v2, v235
	v_fma_f32 v34, v18, v234, -v34
	v_mul_f32_e32 v18, v18, v235
	v_mul_f32_e32 v34, 0x3dd53b94, v34
	v_fmac_f32_e32 v18, v2, v234
	v_cvt_pk_bf16_f32 v38, v34, s0
	v_mad_i64_i32 v[34:35], s[0:1], v83, s85, v[66:67]
	v_mul_f32_e32 v2, 0x3dd53b94, v18
	s_nop 0
	v_cvt_pk_bf16_f32 v2, v2, s0
	global_store_short v[34:35], v2, off offset:64
	v_and_or_b32 v2, v82, 37, v210
	v_cndmask_b32_e32 v2, v2, v82, vcc
	global_store_short v[34:35], v38, off
	v_lshl_or_b32 v34, v2, 5, v69
	v_ashrrev_i32_e32 v35, 31, v34
	v_lshlrev_b64 v[34:35], 2, v[34:35]
	v_lshl_add_u64 v[36:37], s[34:35], 0, v[34:35]
	v_lshl_add_u64 v[34:35], s[36:37], 0, v[34:35]
	global_load_dword v2, v[36:37], off
	global_load_dword v18, v[34:35], off
	v_cmp_gt_i32_e32 vcc, s33, v81
	s_waitcnt vmcnt(0)
	v_mul_f32_e32 v34, v3, v18
	v_fma_f32 v34, v19, v2, -v34
	v_mul_f32_e32 v18, v19, v18
	v_mul_f32_e32 v34, 0x3dd53b94, v34
	v_fmac_f32_e32 v18, v3, v2
	v_cvt_pk_bf16_f32 v36, v34, s0
	v_mad_i64_i32 v[34:35], s[0:1], v82, s85, v[66:67]
	v_mul_f32_e32 v2, 0x3dd53b94, v18
	s_nop 0
	v_cvt_pk_bf16_f32 v2, v2, s0
	global_store_short v[34:35], v2, off offset:64
	v_and_or_b32 v2, v81, 38, v210
	v_cndmask_b32_e32 v2, v2, v81, vcc
	v_lshl_or_b32 v2, v2, 5, v69
	v_ashrrev_i32_e32 v3, 31, v2
	v_lshlrev_b64 v[2:3], 2, v[2:3]
	v_lshl_add_u64 v[18:19], s[34:35], 0, v[2:3]
	v_lshl_add_u64 v[2:3], s[36:37], 0, v[2:3]
	global_load_dword v18, v[18:19], off
	v_cmp_gt_i32_e32 vcc, s33, v80
	global_load_dword v19, v[2:3], off
	s_waitcnt vmcnt(0)
	v_mul_f32_e32 v2, v4, v19
	v_fma_f32 v2, v20, v18, -v2
	v_mul_f32_e32 v19, v20, v19
	v_mul_f32_e32 v2, 0x3dd53b94, v2
	v_fmac_f32_e32 v19, v4, v18
	global_store_short v[34:35], v36, off
	v_cvt_pk_bf16_f32 v34, v2, s0
	v_mad_i64_i32 v[2:3], s[0:1], v81, s85, v[66:67]
	v_mul_f32_e32 v4, 0x3dd53b94, v19
	s_nop 0
	v_cvt_pk_bf16_f32 v4, v4, s0
	global_store_short v[2:3], v34, off
	global_store_short v[2:3], v4, off offset:64
	v_and_or_b32 v2, v80, 39, v210
	v_cndmask_b32_e32 v2, v2, v80, vcc
	v_lshl_or_b32 v2, v2, 5, v69
	v_ashrrev_i32_e32 v3, 31, v2
	v_lshlrev_b64 v[2:3], 2, v[2:3]
	v_lshl_add_u64 v[18:19], s[34:35], 0, v[2:3]
	v_lshl_add_u64 v[2:3], s[36:37], 0, v[2:3]
	global_load_dword v4, v[18:19], off
	v_cmp_gt_i32_e32 vcc, s33, v79
	global_load_dword v18, v[2:3], off
	s_waitcnt vmcnt(0)
; DI u16 f2bf(float x) { return (u16)(pack2(x, 0.f) & 0xffffu); }
; DI int crow(int i, int h) { return (i & 3) + 8 * (i >> 2) + 4 * h; }
; __global__ void __launch_bounds__(256, 2) fwd_megakernel(Params p) {
;     ...
;           if (is_rope) {
; #pragma unroll
;             for (int mt = 0; mt < 2; mt++)
; #pragma unroll
;               for (int i = 0; i < 16; i++) {
;                 const int m = m0 + wm * 64 + mt * 32 + crow(i, h);
;                 const float v0 = acc[mt][0][i], v1 = acc[mt][1][i];
;                 const int pos = tok_pos(m);
;                 const float c = ct[pos * 32 + r], s = st[pos * 32 + r];
;                 Q[(long)m * 1536 + nw0 + r] = f2bf((v0 * c - v1 * s) * QSCALE);
;                 Q[(long)m * 1536 + nw0 + 32 + r] = f2bf((v1 * c + v0 * s) * QSCALE);
;               }
	v_mul_f32_e32 v2, v5, v18
	v_fma_f32 v2, v21, v4, -v2
	v_mul_f32_e32 v18, v21, v18
	v_mul_f32_e32 v2, 0x3dd53b94, v2
	v_fmac_f32_e32 v18, v5, v4
	v_cvt_pk_bf16_f32 v19, v2, s0
	v_mad_i64_i32 v[2:3], s[0:1], v80, s85, v[66:67]
	v_mul_f32_e32 v4, 0x3dd53b94, v18
	s_nop 0
	v_cvt_pk_bf16_f32 v4, v4, s0
	global_store_short v[2:3], v19, off
	global_store_short v[2:3], v4, off offset:64
	v_and_or_b32 v2, v79, 44, v210
	v_cndmask_b32_e32 v2, v2, v79, vcc
	v_lshl_or_b32 v2, v2, 5, v69
	v_ashrrev_i32_e32 v3, 31, v2
	v_lshlrev_b64 v[2:3], 2, v[2:3]
	v_lshl_add_u64 v[4:5], s[34:35], 0, v[2:3]
	v_lshl_add_u64 v[2:3], s[36:37], 0, v[2:3]
	global_load_dword v228, v[4:5], off
	v_cmp_gt_i32_e32 vcc, s33, v78
	global_load_dword v229, v[2:3], off
	v_and_or_b32 v2, v78, 45, v210
	v_cndmask_b32_e32 v2, v2, v78, vcc
	v_lshl_or_b32 v2, v2, 5, v69
	v_ashrrev_i32_e32 v3, 31, v2
	v_lshlrev_b64 v[2:3], 2, v[2:3]
	v_lshl_add_u64 v[4:5], s[34:35], 0, v[2:3]
	v_lshl_add_u64 v[2:3], s[36:37], 0, v[2:3]
	global_load_dword v230, v[4:5], off
	v_cmp_gt_i32_e32 vcc, s33, v77
	global_load_dword v231, v[2:3], off
	v_and_or_b32 v2, v77, 46, v210
	v_cndmask_b32_e32 v2, v2, v77, vcc
	v_lshl_or_b32 v2, v2, 5, v69
	v_ashrrev_i32_e32 v3, 31, v2
	v_lshlrev_b64 v[2:3], 2, v[2:3]
	v_lshl_add_u64 v[4:5], s[34:35], 0, v[2:3]
	v_lshl_add_u64 v[2:3], s[36:37], 0, v[2:3]
	global_load_dword v232, v[4:5], off
	v_cmp_gt_i32_e32 vcc, s33, v76
	global_load_dword v233, v[2:3], off
	v_and_or_b32 v2, v76, 47, v210
	v_cndmask_b32_e32 v2, v2, v76, vcc
	v_lshl_or_b32 v2, v2, 5, v69
	v_ashrrev_i32_e32 v3, 31, v2
	v_lshlrev_b64 v[2:3], 2, v[2:3]
	v_lshl_add_u64 v[4:5], s[34:35], 0, v[2:3]
	v_lshl_add_u64 v[2:3], s[36:37], 0, v[2:3]
	global_load_dword v234, v[4:5], off
	v_cmp_gt_i32_e32 vcc, s33, v75
	global_load_dword v235, v[2:3], off
	v_and_or_b32 v2, v75, 52, v210
	v_cndmask_b32_e32 v2, v2, v75, vcc
	v_lshl_or_b32 v2, v2, 5, v69
	v_ashrrev_i32_e32 v3, 31, v2
	v_lshlrev_b64 v[2:3], 2, v[2:3]
	v_lshl_add_u64 v[4:5], s[34:35], 0, v[2:3]
	v_lshl_add_u64 v[2:3], s[36:37], 0, v[2:3]
	global_load_dword v236, v[4:5], off
	v_cmp_gt_i32_e32 vcc, s33, v74
	global_load_dword v237, v[2:3], off
	v_and_or_b32 v2, v74, 53, v210
	v_cndmask_b32_e32 v2, v2, v74, vcc
	v_lshl_or_b32 v2, v2, 5, v69
	v_ashrrev_i32_e32 v3, 31, v2
	v_lshlrev_b64 v[2:3], 2, v[2:3]
	v_lshl_add_u64 v[4:5], s[34:35], 0, v[2:3]
	v_lshl_add_u64 v[2:3], s[36:37], 0, v[2:3]
	global_load_dword v238, v[4:5], off
	v_cmp_gt_i32_e32 vcc, s33, v73
	global_load_dword v239, v[2:3], off
	s_waitcnt vmcnt(10)
	v_mul_f32_e32 v2, v6, v229
	v_fma_f32 v2, v22, v228, -v2
	v_mul_f32_e32 v5, v22, v229
	v_mul_f32_e32 v2, 0x3dd53b94, v2
	v_fmac_f32_e32 v5, v6, v228
	v_cvt_pk_bf16_f32 v18, v2, s0
	v_mad_i64_i32 v[2:3], s[0:1], v79, s85, v[66:67]
	v_mul_f32_e32 v4, 0x3dd53b94, v5
	s_nop 0
	v_cvt_pk_bf16_f32 v4, v4, s0
	global_store_short v[2:3], v18, off
	global_store_short v[2:3], v4, off offset:64
	v_and_or_b32 v2, v73, 54, v210
	v_cndmask_b32_e32 v2, v2, v73, vcc
	v_lshl_or_b32 v2, v2, 5, v69
	v_ashrrev_i32_e32 v3, 31, v2
	v_lshlrev_b64 v[2:3], 2, v[2:3]
	v_lshl_add_u64 v[4:5], s[34:35], 0, v[2:3]
	v_lshl_add_u64 v[2:3], s[36:37], 0, v[2:3]
	global_load_dword v228, v[4:5], off
	v_cmp_gt_i32_e32 vcc, s33, v72
	global_load_dword v229, v[2:3], off
	s_waitcnt vmcnt(12)
	v_mul_f32_e32 v2, v7, v231
	v_fma_f32 v2, v23, v230, -v2
	v_mul_f32_e32 v5, v23, v231
	v_mul_f32_e32 v2, 0x3dd53b94, v2
	v_fmac_f32_e32 v5, v7, v230
	v_cvt_pk_bf16_f32 v6, v2, s0
	v_mad_i64_i32 v[2:3], s[0:1], v78, s85, v[66:67]
	v_mul_f32_e32 v4, 0x3dd53b94, v5
	s_nop 0
	v_cvt_pk_bf16_f32 v4, v4, s0
	global_store_short v[2:3], v6, off
	global_store_short v[2:3], v4, off offset:64
	v_and_or_b32 v2, v72, 55, v210
	v_cndmask_b32_e32 v2, v2, v72, vcc
	v_lshl_or_b32 v2, v2, 5, v69
	v_ashrrev_i32_e32 v3, 31, v2
	v_lshlrev_b64 v[2:3], 2, v[2:3]
	v_lshl_add_u64 v[4:5], s[34:35], 0, v[2:3]
	v_lshl_add_u64 v[2:3], s[36:37], 0, v[2:3]
	global_load_dword v230, v[4:5], off
	v_cmp_gt_i32_e32 vcc, s33, v71
	global_load_dword v231, v[2:3], off
	s_waitcnt vmcnt(14)
	v_mul_f32_e32 v2, v8, v233
	v_fma_f32 v2, v24, v232, -v2
	v_mul_f32_e32 v5, v24, v233
	v_mul_f32_e32 v2, 0x3dd53b94, v2
	v_fmac_f32_e32 v5, v8, v232
	v_cvt_pk_bf16_f32 v6, v2, s0
	v_mad_i64_i32 v[2:3], s[0:1], v77, s85, v[66:67]
	v_mul_f32_e32 v4, 0x3dd53b94, v5
	s_nop 0
	v_cvt_pk_bf16_f32 v4, v4, s0
	global_store_short v[2:3], v6, off
	global_store_short v[2:3], v4, off offset:64
	v_and_or_b32 v2, v71, 60, v210
	v_cndmask_b32_e32 v2, v2, v71, vcc
	v_lshl_or_b32 v2, v2, 5, v69
	v_ashrrev_i32_e32 v3, 31, v2
	v_lshlrev_b64 v[2:3], 2, v[2:3]
	v_lshl_add_u64 v[4:5], s[34:35], 0, v[2:3]
	v_lshl_add_u64 v[2:3], s[36:37], 0, v[2:3]
	global_load_dword v232, v[4:5], off
	v_cmp_gt_i32_e32 vcc, s33, v70
	global_load_dword v233, v[2:3], off
	s_waitcnt vmcnt(16)
; DI u16 f2bf(float x) { return (u16)(pack2(x, 0.f) & 0xffffu); }
; DI int crow(int i, int h) { return (i & 3) + 8 * (i >> 2) + 4 * h; }
; __global__ void __launch_bounds__(256, 2) fwd_megakernel(Params p) {
;     ...
;           if (is_rope) {
; #pragma unroll
;             for (int mt = 0; mt < 2; mt++)
; #pragma unroll
;               for (int i = 0; i < 16; i++) {
;                 const int m = m0 + wm * 64 + mt * 32 + crow(i, h);
;                 const float v0 = acc[mt][0][i], v1 = acc[mt][1][i];
;                 const int pos = tok_pos(m);
;                 const float c = ct[pos * 32 + r], s = st[pos * 32 + r];
;                 Q[(long)m * 1536 + nw0 + r] = f2bf((v0 * c - v1 * s) * QSCALE);
;                 Q[(long)m * 1536 + nw0 + 32 + r] = f2bf((v1 * c + v0 * s) * QSCALE);
;               }
	v_mul_f32_e32 v2, v9, v235
	v_fma_f32 v2, v25, v234, -v2
	v_mul_f32_e32 v5, v25, v235
	v_mul_f32_e32 v2, 0x3dd53b94, v2
	v_fmac_f32_e32 v5, v9, v234
	v_cvt_pk_bf16_f32 v6, v2, s0
	v_mad_i64_i32 v[2:3], s[0:1], v76, s85, v[66:67]
	v_mul_f32_e32 v4, 0x3dd53b94, v5
	s_nop 0
	v_cvt_pk_bf16_f32 v4, v4, s0
	global_store_short v[2:3], v6, off
	global_store_short v[2:3], v4, off offset:64
	v_and_or_b32 v2, v70, 61, v210
	v_cndmask_b32_e32 v2, v2, v70, vcc
	v_lshl_or_b32 v2, v2, 5, v69
	v_ashrrev_i32_e32 v3, 31, v2
	v_lshlrev_b64 v[2:3], 2, v[2:3]
	v_lshl_add_u64 v[4:5], s[34:35], 0, v[2:3]
	v_lshl_add_u64 v[2:3], s[36:37], 0, v[2:3]
	global_load_dword v234, v[4:5], off
	v_cmp_gt_i32_e32 vcc, s33, v68
	global_load_dword v235, v[2:3], off
	s_waitcnt vmcnt(18)
	v_mul_f32_e32 v2, v10, v237
	v_fma_f32 v2, v26, v236, -v2
	v_mul_f32_e32 v5, v26, v237
	v_mul_f32_e32 v2, 0x3dd53b94, v2
	v_fmac_f32_e32 v5, v10, v236
	v_cvt_pk_bf16_f32 v6, v2, s0
	v_mad_i64_i32 v[2:3], s[0:1], v75, s85, v[66:67]
	v_mul_f32_e32 v4, 0x3dd53b94, v5
	s_nop 0
	v_cvt_pk_bf16_f32 v4, v4, s0
	global_store_short v[2:3], v6, off
	global_store_short v[2:3], v4, off offset:64
	v_and_or_b32 v2, v68, 62, v210
	v_cndmask_b32_e32 v2, v2, v68, vcc
	v_lshl_or_b32 v2, v2, 5, v69
	v_ashrrev_i32_e32 v3, 31, v2
	v_lshlrev_b64 v[2:3], 2, v[2:3]
	v_lshl_add_u64 v[4:5], s[34:35], 0, v[2:3]
	v_lshl_add_u64 v[2:3], s[36:37], 0, v[2:3]
	global_load_dword v236, v[4:5], off
	v_cmp_gt_i32_e32 vcc, s33, v0
	global_load_dword v237, v[2:3], off
	s_waitcnt vmcnt(20)
	v_mul_f32_e32 v2, v11, v239
	v_fma_f32 v2, v27, v238, -v2
	v_mul_f32_e32 v5, v27, v239
	v_mul_f32_e32 v2, 0x3dd53b94, v2
	v_fmac_f32_e32 v5, v11, v238
	v_cvt_pk_bf16_f32 v6, v2, s0
	v_mad_i64_i32 v[2:3], s[0:1], v74, s85, v[66:67]
	v_mul_f32_e32 v4, 0x3dd53b94, v5
	s_nop 0
	v_cvt_pk_bf16_f32 v4, v4, s0
	global_store_short v[2:3], v6, off
	global_store_short v[2:3], v4, off offset:64
	v_and_or_b32 v2, v0, 63, v210
	v_cndmask_b32_e32 v2, v2, v0, vcc
	v_lshl_or_b32 v2, v2, 5, v69
	v_ashrrev_i32_e32 v3, 31, v2
	v_lshlrev_b64 v[2:3], 2, v[2:3]
	v_lshl_add_u64 v[4:5], s[34:35], 0, v[2:3]
	v_lshl_add_u64 v[2:3], s[36:37], 0, v[2:3]
	global_load_dword v238, v[4:5], off
	s_nop 0
	global_load_dword v239, v[2:3], off
	s_waitcnt vmcnt(20)
	v_mul_f32_e32 v2, v12, v229
	v_fma_f32 v2, v28, v228, -v2
	v_mul_f32_e32 v5, v28, v229
	v_mul_f32_e32 v2, 0x3dd53b94, v2
	v_fmac_f32_e32 v5, v12, v228
	v_cvt_pk_bf16_f32 v6, v2, s0
	v_mad_i64_i32 v[2:3], s[0:1], v73, s85, v[66:67]
	v_mul_f32_e32 v4, 0x3dd53b94, v5
	s_nop 0
	v_cvt_pk_bf16_f32 v4, v4, s0
	global_store_short v[2:3], v6, off
	global_store_short v[2:3], v4, off offset:64
	s_waitcnt vmcnt(18)
	v_mul_f32_e32 v2, v13, v231
	v_fma_f32 v2, v29, v230, -v2
	v_mul_f32_e32 v5, v29, v231
	v_mul_f32_e32 v2, 0x3dd53b94, v2
	v_fmac_f32_e32 v5, v13, v230
	v_cvt_pk_bf16_f32 v6, v2, s0
	v_mad_i64_i32 v[2:3], s[0:1], v72, s85, v[66:67]
	v_mul_f32_e32 v4, 0x3dd53b94, v5
	s_nop 0
	v_cvt_pk_bf16_f32 v4, v4, s0
	global_store_short v[2:3], v6, off
	global_store_short v[2:3], v4, off offset:64
	s_waitcnt vmcnt(16)
	v_mul_f32_e32 v2, v14, v233
	v_fma_f32 v2, v30, v232, -v2
	v_mul_f32_e32 v5, v30, v233
	v_mul_f32_e32 v2, 0x3dd53b94, v2
	v_fmac_f32_e32 v5, v14, v232
	v_cvt_pk_bf16_f32 v6, v2, s0
	v_mad_i64_i32 v[2:3], s[0:1], v71, s85, v[66:67]
	v_mul_f32_e32 v4, 0x3dd53b94, v5
	s_nop 0
	v_cvt_pk_bf16_f32 v4, v4, s0
	global_store_short v[2:3], v6, off
	global_store_short v[2:3], v4, off offset:64
	s_waitcnt vmcnt(14)
	v_mul_f32_e32 v2, v15, v235
	v_fma_f32 v2, v31, v234, -v2
	v_mul_f32_e32 v5, v31, v235
	v_mul_f32_e32 v2, 0x3dd53b94, v2
	v_fmac_f32_e32 v5, v15, v234
	v_cvt_pk_bf16_f32 v6, v2, s0
	v_mad_i64_i32 v[2:3], s[0:1], v70, s85, v[66:67]
	v_mul_f32_e32 v4, 0x3dd53b94, v5
	s_nop 0
	v_cvt_pk_bf16_f32 v4, v4, s0
	global_store_short v[2:3], v6, off
	global_store_short v[2:3], v4, off offset:64
	s_waitcnt vmcnt(12)
	v_mul_f32_e32 v2, v16, v237
	v_fma_f32 v2, v32, v236, -v2
	v_mul_f32_e32 v5, v32, v237
	v_mul_f32_e32 v2, 0x3dd53b94, v2
	v_fmac_f32_e32 v5, v16, v236
	v_cvt_pk_bf16_f32 v6, v2, s0
	v_mad_i64_i32 v[2:3], s[0:1], v68, s85, v[66:67]
	v_mul_f32_e32 v4, 0x3dd53b94, v5
	s_nop 0
	v_cvt_pk_bf16_f32 v4, v4, s0
	global_store_short v[2:3], v6, off
	global_store_short v[2:3], v4, off offset:64
	s_waitcnt vmcnt(10)
	v_mul_f32_e32 v2, v17, v239
	v_fma_f32 v2, v33, v238, -v2
	v_mul_f32_e32 v2, 0x3dd53b94, v2
	v_cvt_pk_bf16_f32 v6, v2, s0
	v_mad_i64_i32 v[2:3], s[0:1], v0, s85, v[66:67]
	v_mul_f32_e32 v0, v33, v239
	v_fmac_f32_e32 v0, v17, v238
	v_mul_f32_e32 v0, 0x3dd53b94, v0
	v_cvt_pk_bf16_f32 v0, v0, s0
	global_store_short v[2:3], v6, off
	global_store_short v[2:3], v0, off offset:64
	s_branch .LBB0_548
